# row sum-of-squares in FFN_IN/LRU_IN epilogues computed cooperatively (8 loads/lane + ds_bpermute broadcast) instead of 36 loads + 112 adds per lane; plus lru_final prefix batching
# speedup vs baseline: 1.0252x; 1.0148x over previous
.LBB0_754:
	v_add_u32_e32 v82, s60, v93
	v_and_b32_e32 v226, 31, v199
	v_bfe_u32 v227, v199, 5, 1
	v_lshlrev_b32_e32 v229, 2, v227
	v_sub_u32_e32 v226, v226, v229
	v_add_lshl_u32 v226, v226, v82, 2
	v_lshlrev_b32_e32 v227, 4, v227
	global_load_dword v218, v226, s[6:7]
	v_add_u32_e32 v229, 0x10000, v226
	global_load_dword v219, v229, s[6:7]
	v_add_u32_e32 v229, 0x20000, v226
	global_load_dword v220, v229, s[6:7]
	v_add_u32_e32 v229, 0x30000, v226
	global_load_dword v221, v229, s[6:7]
	v_add_u32_e32 v229, 0x40000, v226
	global_load_dword v222, v229, s[6:7]
	v_add_u32_e32 v229, 0x50000, v226
	global_load_dword v223, v229, s[6:7]
	v_add_u32_e32 v229, 0x60000, v226
	global_load_dword v224, v229, s[6:7]
	v_add_u32_e32 v229, 0x70000, v226
	global_load_dword v225, v229, s[6:7]
	s_waitcnt vmcnt(0)
	v_add_f32_e32 v218, v218, v219
	v_add_f32_e32 v220, v220, v221
	v_add_f32_e32 v222, v222, v223
	v_add_f32_e32 v224, v224, v225
	v_add_f32_e32 v218, v218, v220
	v_add_f32_e32 v222, v222, v224
	v_add_f32_e32 v218, v218, v222
	v_fmamk_f32 v218, v218, 0x3a800000, v118
	v_rsq_f32_e32 v218, v218
	s_nop 1
	ds_bpermute_b32 v230, v227, v218
	ds_bpermute_b32 v231, v227, v218 offset:4
	ds_bpermute_b32 v232, v227, v218 offset:8
	ds_bpermute_b32 v233, v227, v218 offset:12
	ds_bpermute_b32 v234, v227, v218 offset:32
	ds_bpermute_b32 v235, v227, v218 offset:36
	ds_bpermute_b32 v236, v227, v218 offset:40
	ds_bpermute_b32 v237, v227, v218 offset:44
	ds_bpermute_b32 v238, v227, v218 offset:64
	ds_bpermute_b32 v239, v227, v218 offset:68
	ds_bpermute_b32 v240, v227, v218 offset:72
	ds_bpermute_b32 v241, v227, v218 offset:76
	ds_bpermute_b32 v242, v227, v218 offset:96
	ds_bpermute_b32 v243, v227, v218 offset:100
	ds_bpermute_b32 v244, v227, v218 offset:104
	ds_bpermute_b32 v245, v227, v218 offset:108
	s_waitcnt lgkmcnt(0)
	v_or_b32_e32 v84, 8, v82
	s_add_i32 s59, s60, 0xffffe000
	s_lshr_b32 s59, s59, 12
	s_mulk_i32 s59, 0x1600
	s_addk_i32 s59, 0x1600
	s_cmp_gt_i32 s4, 63
	s_cselect_b32 s4, s59, 0
	s_lshl_b64 s[60:61], s[4:5], 2
	s_add_u32 s60, s10, s60
	s_addc_u32 s61, s11, s61
	v_or_b32_e32 v120, 1, v82
	v_or_b32_e32 v119, 2, v82
	v_or_b32_e32 v83, 3, v82
	s_add_i32 s3, s3, s33
	s_cmpk_gt_i32 s3, 0x15ff
	v_or_b32_e32 v68, 9, v82
	v_or_b32_e32 v64, 16, v82
	v_mov_b32_e32 v71, v233
	v_or_b32_e32 v85, 10, v82
	v_or_b32_e32 v121, 18, v82
	v_or_b32_e32 v88, 17, v82
	v_or_b32_e32 v86, 24, v82
	v_ashrrev_i32_e32 v87, 31, v86
	v_lshl_add_u64 v[90:91], v[86:87], 2, s[6:7]
	v_or_b32_e32 v87, 11, v82
	v_add_co_u32_e32 v90, vcc, s75, v90
	s_nop 1
	v_addc_co_u32_e32 v91, vcc, 0, v91, vcc
	v_or_b32_e32 v90, 25, v82
	v_mov_b32_e32 v72, v234
	v_or_b32_e32 v66, s58, v92
	v_ashrrev_i32_e32 v67, 31, v66
	v_lshl_add_u64 v[66:67], v[66:67], 2, s[60:61]
	global_load_dword v122, v[66:67], off
	global_load_dword v65, v[66:67], off offset:128
	v_mov_b32_e32 v73, v235
	v_mov_b32_e32 v74, v236
	global_load_dword v126, v[66:67], off offset:256
	global_load_dword v66, v[66:67], off offset:384
	v_mov_b32_e32 v67, v230
	v_mov_b32_e32 v70, v231
	v_mov_b32_e32 v75, v237
	v_mov_b32_e32 v89, v238
	v_mov_b32_e32 v91, v239
	v_mov_b32_e32 v123, v240
	v_mov_b32_e32 v125, v241
	v_mov_b32_e32 v69, v242
	v_or_b32_e32 v124, 19, v82
	v_mov_b32_e32 v132, v232
	v_mov_b32_e32 v127, v243
	v_mov_b32_e32 v129, v244
	v_mov_b32_e32 v131, v245
	v_or_b32_e32 v128, 26, v82
	v_or_b32_e32 v130, 27, v82
	s_waitcnt vmcnt(3)
	v_fma_f32 v48, v48, v67, v122
	v_fma_f32 v49, v49, v70, v122
	s_waitcnt vmcnt(2)
	v_fma_f32 v32, v32, v67, v65
	v_fma_f32 v33, v33, v70, v65
	v_fma_f32 v34, v34, v132, v65
	v_fma_f32 v35, v35, v71, v65
	v_fma_f32 v36, v36, v72, v65
	v_fma_f32 v37, v37, v73, v65
	v_fma_f32 v38, v38, v74, v65
	v_fma_f32 v39, v39, v75, v65
	v_fma_f32 v40, v40, v89, v65
	v_fma_f32 v41, v41, v91, v65
	v_fma_f32 v42, v42, v123, v65
	v_fma_f32 v43, v43, v125, v65
	v_fma_f32 v44, v44, v69, v65
	v_fma_f32 v45, v45, v127, v65
	v_fma_f32 v46, v46, v129, v65
	v_fmac_f32_e32 v65, v47, v131
	s_waitcnt vmcnt(0)
	v_fma_f32 v47, v0, v67, v66
	v_mul_f32_e32 v0, 0xbfb8aa3b, v48
	v_fma_f32 v16, v16, v67, v126
	v_fma_f32 v67, v2, v132, v66
	v_exp_f32_e32 v2, v0
	v_fma_f32 v50, v50, v132, v122
	v_fma_f32 v51, v51, v71, v122
	v_fma_f32 v52, v52, v72, v122
	v_add_f32_e32 v2, 1.0, v2
	v_rcp_f32_e32 v2, v2
	v_fma_f32 v53, v53, v73, v122
	v_fma_f32 v54, v54, v74, v122
	v_fma_f32 v55, v55, v75, v122
	v_fma_f32 v56, v56, v89, v122
	v_fma_f32 v57, v57, v91, v122
	v_fma_f32 v58, v58, v123, v122
	v_fma_f32 v59, v59, v125, v122
	v_fma_f32 v60, v60, v69, v122
	v_fma_f32 v61, v61, v127, v122
	v_fma_f32 v62, v62, v129, v122
	v_fmac_f32_e32 v122, v63, v131
	v_fma_f32 v17, v17, v70, v126
	v_fma_f32 v63, v1, v70, v66
	v_fma_f32 v70, v3, v71, v66
	v_mul_f32_e32 v3, 0xbfb8aa3b, v49
	v_exp_f32_e32 v3, v3
	v_mul_f32_e32 v2, v48, v2
	v_mul_f32_e32 v2, v16, v2
	v_fma_f32 v19, v19, v71, v126
	v_fma_f32 v71, v4, v72, v66
	v_cvt_pk_bf16_f32 v4, v2, s0
	v_add_f32_e32 v2, 1.0, v3
	v_fma_f32 v20, v20, v72, v126
	v_fma_f32 v72, v5, v73, v66
	v_lshl_or_b32 v0, s76, 6, v92
	v_rcp_f32_e32 v5, v2
	v_ashrrev_i32_e32 v1, 31, v0
	v_lshl_add_u64 v[0:1], v[0:1], 1, s[8:9]
	v_mad_i64_i32 v[2:3], s[58:59], v82, s68, v[0:1]
	global_store_short v[2:3], v4, off sc1
	v_mul_f32_e32 v4, v49, v5
	v_mul_f32_e32 v5, 0xbfb8aa3b, v50
	v_fma_f32 v21, v21, v73, v126
	v_fma_f32 v73, v6, v74, v66
	v_exp_f32_e32 v6, v5
	v_mul_f32_e32 v4, v17, v4
	v_fma_f32 v22, v22, v74, v126
	v_fma_f32 v74, v7, v75, v66
	v_add_f32_e32 v6, 1.0, v6
	v_cvt_pk_bf16_f32 v7, v4, s0
	v_mad_i64_i32 v[4:5], s[58:59], v120, s68, v[0:1]
	v_rcp_f32_e32 v6, v6
	global_store_short v[4:5], v7, off sc1
	v_mul_f32_e32 v7, 0xbfb8aa3b, v51
	v_exp_f32_e32 v7, v7
	v_fma_f32 v18, v18, v132, v126
	v_mul_f32_e32 v6, v50, v6
	v_mul_f32_e32 v6, v18, v6
	v_fma_f32 v23, v23, v75, v126
	v_fma_f32 v75, v8, v89, v66
	v_cvt_pk_bf16_f32 v8, v6, s0
	v_add_f32_e32 v6, 1.0, v7
	v_fma_f32 v24, v24, v89, v126
	v_fma_f32 v89, v9, v91, v66
	v_rcp_f32_e32 v9, v6
	v_mad_i64_i32 v[6:7], s[58:59], v119, s68, v[0:1]
	global_store_short v[6:7], v8, off sc1
	v_mul_f32_e32 v8, v51, v9
	v_mul_f32_e32 v9, 0xbfb8aa3b, v52
	v_fma_f32 v25, v25, v91, v126
	v_fma_f32 v91, v10, v123, v66
	v_exp_f32_e32 v10, v9
	v_mul_f32_e32 v8, v19, v8
	v_fma_f32 v26, v26, v123, v126
	v_fma_f32 v123, v11, v125, v66
	v_add_f32_e32 v10, 1.0, v10
	v_cvt_pk_bf16_f32 v11, v8, s0
	v_mad_i64_i32 v[8:9], s[58:59], v83, s68, v[0:1]
	v_rcp_f32_e32 v10, v10
	global_store_short v[8:9], v11, off sc1
	v_mul_f32_e32 v11, 0xbfb8aa3b, v53
	v_exp_f32_e32 v11, v11
	v_mul_f32_e32 v10, v52, v10
	v_mul_f32_e32 v10, v20, v10
	v_fma_f32 v28, v28, v69, v126
	v_fma_f32 v69, v12, v69, v66
	v_cvt_pk_bf16_f32 v12, v10, s0
	v_add_f32_e32 v10, 1.0, v11
	v_fma_f32 v27, v27, v125, v126
	v_fma_f32 v125, v13, v127, v66
	v_rcp_f32_e32 v13, v10
	v_mad_i64_i32 v[10:11], s[58:59], v84, s68, v[0:1]
	global_store_short v[10:11], v12, off sc1
	v_mul_f32_e32 v12, v53, v13
	v_mul_f32_e32 v13, 0xbfb8aa3b, v54
	v_fma_f32 v29, v29, v127, v126
	v_fma_f32 v127, v14, v129, v66
	v_exp_f32_e32 v14, v13
	v_mul_f32_e32 v12, v21, v12
	v_fmac_f32_e32 v66, v15, v131
	v_cvt_pk_bf16_f32 v15, v12, s0
	v_add_f32_e32 v14, 1.0, v14
	v_mad_i64_i32 v[12:13], s[58:59], v68, s68, v[0:1]
	v_rcp_f32_e32 v14, v14
	global_store_short v[12:13], v15, off sc1
	v_mul_f32_e32 v15, 0xbfb8aa3b, v55
	v_exp_f32_e32 v15, v15
	v_mul_f32_e32 v14, v54, v14
	v_mul_f32_e32 v14, v22, v14
	v_cvt_pk_bf16_f32 v16, v14, s0
	v_add_f32_e32 v14, 1.0, v15
	v_rcp_f32_e32 v17, v14
	v_mad_i64_i32 v[14:15], s[58:59], v85, s68, v[0:1]
	global_store_short v[14:15], v16, off sc1
	v_mul_f32_e32 v16, v55, v17
	v_mul_f32_e32 v17, 0xbfb8aa3b, v56
	v_exp_f32_e32 v18, v17
	v_mul_f32_e32 v16, v23, v16
	v_cvt_pk_bf16_f32 v19, v16, s0
	v_mad_i64_i32 v[16:17], s[58:59], v87, s68, v[0:1]
	v_add_f32_e32 v18, 1.0, v18
	v_rcp_f32_e32 v18, v18
	global_store_short v[16:17], v19, off sc1
	v_mul_f32_e32 v19, 0xbfb8aa3b, v57
	v_exp_f32_e32 v19, v19
	v_mul_f32_e32 v18, v56, v18
	v_mul_f32_e32 v18, v24, v18
	v_cvt_pk_bf16_f32 v20, v18, s0
	v_add_f32_e32 v18, 1.0, v19
	v_rcp_f32_e32 v21, v18
	v_mad_i64_i32 v[18:19], s[58:59], v64, s68, v[0:1]
	global_store_short v[18:19], v20, off sc1
	v_mul_f32_e32 v20, v57, v21
	v_mul_f32_e32 v21, 0xbfb8aa3b, v58
	v_exp_f32_e32 v22, v21
	v_mul_f32_e32 v20, v25, v20
	v_cvt_pk_bf16_f32 v23, v20, s0
	v_mad_i64_i32 v[20:21], s[58:59], v88, s68, v[0:1]
	v_add_f32_e32 v22, 1.0, v22
	v_rcp_f32_e32 v22, v22
	global_store_short v[20:21], v23, off sc1
	v_mul_f32_e32 v23, 0xbfb8aa3b, v59
	v_exp_f32_e32 v23, v23
	v_mul_f32_e32 v22, v58, v22
	v_mul_f32_e32 v22, v26, v22
	v_cvt_pk_bf16_f32 v24, v22, s0
	v_add_f32_e32 v22, 1.0, v23
	v_rcp_f32_e32 v25, v22
	v_mad_i64_i32 v[22:23], s[58:59], v121, s68, v[0:1]
	global_store_short v[22:23], v24, off sc1
	v_mul_f32_e32 v24, v59, v25
	v_mul_f32_e32 v25, 0xbfb8aa3b, v60
	v_exp_f32_e32 v26, v25
	v_mul_f32_e32 v24, v27, v24
	v_cvt_pk_bf16_f32 v27, v24, s0
	v_mad_i64_i32 v[24:25], s[58:59], v124, s68, v[0:1]
	v_add_f32_e32 v26, 1.0, v26
	v_rcp_f32_e32 v26, v26
	global_store_short v[24:25], v27, off sc1
	v_mul_f32_e32 v27, 0xbfb8aa3b, v61
	v_exp_f32_e32 v27, v27
	v_mul_f32_e32 v26, v60, v26
	v_mul_f32_e32 v26, v28, v26
	v_cvt_pk_bf16_f32 v28, v26, s0
	v_add_f32_e32 v26, 1.0, v27
	v_fma_f32 v30, v30, v129, v126
	v_fmac_f32_e32 v126, v31, v131
	v_rcp_f32_e32 v31, v26
	v_mad_i64_i32 v[26:27], s[58:59], v86, s68, v[0:1]
	global_store_short v[26:27], v28, off sc1
	v_mul_f32_e32 v28, v61, v31
	v_mul_f32_e32 v28, v29, v28
	v_mul_f32_e32 v29, 0xbfb8aa3b, v62
	v_exp_f32_e32 v31, v29
	v_cvt_pk_bf16_f32 v48, v28, s0
	v_mad_i64_i32 v[28:29], s[58:59], v90, s68, v[0:1]
	v_add_f32_e32 v31, 1.0, v31
	v_rcp_f32_e32 v31, v31
	global_store_short v[28:29], v48, off sc1
	v_mul_f32_e32 v48, 0xbfb8aa3b, v122
	v_exp_f32_e32 v48, v48
	v_mul_f32_e32 v31, v62, v31
	v_mul_f32_e32 v30, v30, v31
	v_cvt_pk_bf16_f32 v49, v30, s0
	v_add_f32_e32 v30, 1.0, v48
	v_rcp_f32_e32 v48, v30
	v_mad_i64_i32 v[30:31], s[58:59], v128, s68, v[0:1]
	global_store_short v[30:31], v49, off sc1
	v_mul_f32_e32 v49, 0xbfb8aa3b, v32
	v_exp_f32_e32 v49, v49
	v_mul_f32_e32 v48, v122, v48
	v_mul_f32_e32 v48, v126, v48
	v_cvt_pk_bf16_f32 v48, v48, s0
	v_mad_i64_i32 v[0:1], s[58:59], v130, s68, v[0:1]
	v_add_f32_e32 v49, 1.0, v49
	v_rcp_f32_e32 v49, v49
	global_store_short v[0:1], v48, off sc1
	v_mul_f32_e32 v48, 0xbfb8aa3b, v33
	v_exp_f32_e32 v48, v48
	v_mul_f32_e32 v32, v32, v49
	v_mul_f32_e32 v32, v47, v32
	v_cvt_pk_bf16_f32 v32, v32, s0
	v_add_f32_e32 v47, 1.0, v48
	v_rcp_f32_e32 v47, v47
	global_store_short v[2:3], v32, off offset:64 sc1
	v_mul_f32_e32 v2, 0xbfb8aa3b, v34
	v_exp_f32_e32 v2, v2
	v_mul_f32_e32 v3, v33, v47
	v_mul_f32_e32 v3, v63, v3
	v_cvt_pk_bf16_f32 v3, v3, s0
	global_store_short v[4:5], v3, off offset:64 sc1
	v_mul_f32_e32 v3, 0xbfb8aa3b, v35
	v_exp_f32_e32 v3, v3
	v_add_f32_e32 v2, 1.0, v2
	v_rcp_f32_e32 v2, v2
	v_mul_f32_e32 v4, 0xbfb8aa3b, v46
	v_add_f32_e32 v3, 1.0, v3
	v_rcp_f32_e32 v3, v3
	v_mul_f32_e32 v2, v34, v2
	v_mul_f32_e32 v2, v67, v2
	v_cvt_pk_bf16_f32 v2, v2, s0
	global_store_short v[6:7], v2, off offset:64 sc1
	v_mul_f32_e32 v2, 0xbfb8aa3b, v36
	v_mul_f32_e32 v3, v35, v3
	v_exp_f32_e32 v2, v2
	v_mul_f32_e32 v3, v70, v3
	v_cvt_pk_bf16_f32 v3, v3, s0
	global_store_short v[8:9], v3, off offset:64 sc1
	v_mul_f32_e32 v3, 0xbfb8aa3b, v37
	v_exp_f32_e32 v3, v3
	v_add_f32_e32 v2, 1.0, v2
	v_rcp_f32_e32 v2, v2
	v_exp_f32_e32 v4, v4
	v_add_f32_e32 v3, 1.0, v3
	v_rcp_f32_e32 v3, v3
	v_mul_f32_e32 v2, v36, v2
	v_mul_f32_e32 v2, v71, v2
	v_cvt_pk_bf16_f32 v2, v2, s0
	global_store_short v[10:11], v2, off offset:64 sc1
	v_mul_f32_e32 v2, 0xbfb8aa3b, v38
	v_mul_f32_e32 v3, v37, v3
	v_exp_f32_e32 v2, v2
	v_mul_f32_e32 v3, v72, v3
	v_cvt_pk_bf16_f32 v3, v3, s0
	global_store_short v[12:13], v3, off offset:64 sc1
	v_mul_f32_e32 v3, 0xbfb8aa3b, v39
	v_exp_f32_e32 v3, v3
	v_add_f32_e32 v2, 1.0, v2
	v_rcp_f32_e32 v2, v2
	v_add_f32_e32 v3, 1.0, v3
	v_rcp_f32_e32 v3, v3
	v_mul_f32_e32 v2, v38, v2
	v_mul_f32_e32 v2, v73, v2
	v_cvt_pk_bf16_f32 v2, v2, s0
	global_store_short v[14:15], v2, off offset:64 sc1
	v_mul_f32_e32 v2, 0xbfb8aa3b, v40
	v_mul_f32_e32 v3, v39, v3
	v_exp_f32_e32 v2, v2
	v_mul_f32_e32 v3, v74, v3
	v_cvt_pk_bf16_f32 v3, v3, s0
	global_store_short v[16:17], v3, off offset:64 sc1
	v_mul_f32_e32 v3, 0xbfb8aa3b, v41
	v_exp_f32_e32 v3, v3
	v_add_f32_e32 v2, 1.0, v2
	v_rcp_f32_e32 v2, v2
	v_add_f32_e32 v3, 1.0, v3
	v_rcp_f32_e32 v3, v3
	v_mul_f32_e32 v2, v40, v2
	v_mul_f32_e32 v2, v75, v2
	v_cvt_pk_bf16_f32 v2, v2, s0
	global_store_short v[18:19], v2, off offset:64 sc1
	v_mul_f32_e32 v2, 0xbfb8aa3b, v42
	v_mul_f32_e32 v3, v41, v3
	v_exp_f32_e32 v2, v2
	v_mul_f32_e32 v3, v89, v3
	v_cvt_pk_bf16_f32 v3, v3, s0
	global_store_short v[20:21], v3, off offset:64 sc1
	v_mul_f32_e32 v3, 0xbfb8aa3b, v43
	v_exp_f32_e32 v3, v3
	v_add_f32_e32 v2, 1.0, v2
	v_rcp_f32_e32 v2, v2
	v_add_f32_e32 v3, 1.0, v3
	v_rcp_f32_e32 v3, v3
	v_mul_f32_e32 v2, v42, v2
	v_mul_f32_e32 v2, v91, v2
	v_cvt_pk_bf16_f32 v2, v2, s0
	global_store_short v[22:23], v2, off offset:64 sc1
	v_mul_f32_e32 v2, 0xbfb8aa3b, v44
	v_mul_f32_e32 v3, v43, v3
	v_exp_f32_e32 v2, v2
	v_mul_f32_e32 v3, v123, v3
	v_cvt_pk_bf16_f32 v3, v3, s0
	global_store_short v[24:25], v3, off offset:64 sc1
	v_mul_f32_e32 v3, 0xbfb8aa3b, v45
	v_exp_f32_e32 v3, v3
	v_add_f32_e32 v2, 1.0, v2
	v_rcp_f32_e32 v2, v2
	v_add_f32_e32 v3, 1.0, v3
	v_rcp_f32_e32 v3, v3
	v_mul_f32_e32 v2, v44, v2
	v_mul_f32_e32 v2, v69, v2
	v_cvt_pk_bf16_f32 v2, v2, s0
	global_store_short v[26:27], v2, off offset:64 sc1
	v_mul_f32_e32 v2, v45, v3
	v_add_f32_e32 v3, 1.0, v4
	v_mul_f32_e32 v4, 0xbfb8aa3b, v65
	v_rcp_f32_e32 v3, v3
	v_exp_f32_e32 v4, v4
	v_mul_f32_e32 v2, v125, v2
	v_cvt_pk_bf16_f32 v2, v2, s0
	global_store_short v[28:29], v2, off offset:64 sc1
	v_mul_f32_e32 v2, v46, v3
	v_add_f32_e32 v3, 1.0, v4
	v_rcp_f32_e32 v3, v3
	v_mul_f32_e32 v2, v127, v2
	v_cvt_pk_bf16_f32 v2, v2, s0
	global_store_short v[30:31], v2, off offset:64 sc1
	v_mul_f32_e32 v2, v65, v3
	v_mul_f32_e32 v2, v66, v2
	v_cvt_pk_bf16_f32 v2, v2, s0
	global_store_short v[0:1], v2, off offset:64 sc1
	s_cbranch_scc1 .LBB0_759

.LBB0_1450:
	v_add_u32_e32 v82, s62, v95
	v_and_b32_e32 v226, 31, v199
	v_bfe_u32 v227, v199, 5, 1
	v_lshlrev_b32_e32 v229, 2, v227
	v_sub_u32_e32 v226, v226, v229
	v_add_lshl_u32 v226, v226, v82, 2
	v_lshlrev_b32_e32 v227, 4, v227
	global_load_dword v218, v226, s[6:7]
	v_add_u32_e32 v229, 0x10000, v226
	global_load_dword v219, v229, s[6:7]
	v_add_u32_e32 v229, 0x20000, v226
	global_load_dword v220, v229, s[6:7]
	v_add_u32_e32 v229, 0x30000, v226
	global_load_dword v221, v229, s[6:7]
	v_add_u32_e32 v229, 0x40000, v226
	global_load_dword v222, v229, s[6:7]
	v_add_u32_e32 v229, 0x50000, v226
	global_load_dword v223, v229, s[6:7]
	v_add_u32_e32 v229, 0x60000, v226
	global_load_dword v224, v229, s[6:7]
	v_add_u32_e32 v229, 0x70000, v226
	global_load_dword v225, v229, s[6:7]
	s_waitcnt vmcnt(0)
	v_add_f32_e32 v218, v218, v219
	v_add_f32_e32 v220, v220, v221
	v_add_f32_e32 v222, v222, v223
	v_add_f32_e32 v224, v224, v225
	v_add_f32_e32 v218, v218, v220
	v_add_f32_e32 v222, v222, v224
	v_add_f32_e32 v218, v218, v222
	v_fmamk_f32 v218, v218, 0x3a800000, v121
	v_rsq_f32_e32 v218, v218
	s_nop 1
	ds_bpermute_b32 v230, v227, v218
	ds_bpermute_b32 v231, v227, v218 offset:4
	ds_bpermute_b32 v232, v227, v218 offset:8
	ds_bpermute_b32 v233, v227, v218 offset:12
	ds_bpermute_b32 v234, v227, v218 offset:32
	ds_bpermute_b32 v235, v227, v218 offset:36
	ds_bpermute_b32 v236, v227, v218 offset:40
	ds_bpermute_b32 v237, v227, v218 offset:44
	ds_bpermute_b32 v238, v227, v218 offset:64
	ds_bpermute_b32 v239, v227, v218 offset:68
	ds_bpermute_b32 v240, v227, v218 offset:72
	ds_bpermute_b32 v241, v227, v218 offset:76
	ds_bpermute_b32 v242, v227, v218 offset:96
	ds_bpermute_b32 v243, v227, v218 offset:100
	ds_bpermute_b32 v244, v227, v218 offset:104
	ds_bpermute_b32 v245, v227, v218 offset:108
	s_waitcnt lgkmcnt(0)
	v_or_b32_e32 v84, 8, v82
	s_add_i32 s61, s62, 0xffffe000
	s_lshr_b32 s61, s61, 12
	s_mulk_i32 s61, 0xc00
	s_addk_i32 s61, 0xc00
	s_cmp_gt_i32 s4, 63
	s_cselect_b32 s4, s61, 0
	s_lshl_b64 s[62:63], s[4:5], 2
	s_add_u32 s62, s10, s62
	s_addc_u32 s63, s11, s63
	v_or_b32_e32 v123, 1, v82
	v_or_b32_e32 v125, 2, v82
	v_or_b32_e32 v127, 3, v82
	s_cmp_gt_i32 s77, 63
	v_or_b32_e32 v86, 16, v82
	v_or_b32_e32 v68, 9, v82
	v_or_b32_e32 v88, 17, v82
	v_or_b32_e32 v90, 24, v82
	v_ashrrev_i32_e32 v91, 31, v90
	v_lshl_add_u64 v[92:93], v[90:91], 2, s[6:7]
	v_add_co_u32_e32 v92, vcc, s76, v92
	s_nop 1
	v_addc_co_u32_e32 v93, vcc, 0, v93, vcc
	v_or_b32_e32 v92, 25, v82
	v_or_b32_e32 v129, 10, v82
	v_or_b32_e32 v130, 11, v82
	v_or_b32_e32 v131, 18, v82
	v_or_b32_e32 v132, 19, v82
	v_or_b32_e32 v133, 26, v82
	v_or_b32_e32 v64, s60, v94
	v_ashrrev_i32_e32 v65, 31, v64
	v_lshl_add_u64 v[70:71], v[64:65], 2, s[62:63]
	global_load_dword v69, v[70:71], off
	global_load_dword v67, v[70:71], off offset:128
	s_mov_b64 s[62:63], -1
	global_load_dword v66, v[70:71], off offset:256
	global_load_dword v65, v[70:71], off offset:384
	v_mov_b32_e32 v137, v231
	v_mov_b32_e32 v138, v232
	v_mov_b32_e32 v139, v233
	v_mov_b32_e32 v140, v234
	v_mov_b32_e32 v141, v235
	v_mov_b32_e32 v142, v236
	v_mov_b32_e32 v143, v237
	v_mov_b32_e32 v144, v238
	v_mov_b32_e32 v145, v239
	v_mov_b32_e32 v146, v240
	v_mov_b32_e32 v147, v241
	v_mov_b32_e32 v148, v242
	v_mov_b32_e32 v149, v243
	v_mov_b32_e32 v150, v244
	v_mov_b32_e32 v136, v230
	v_mov_b32_e32 v128, v245
	v_or_b32_e32 v134, 27, v82
	s_waitcnt vmcnt(3)
	v_fma_f32 v126, v48, v136, v69
	v_fma_f32 v124, v49, v137, v69
	v_fma_f32 v122, v50, v138, v69
	v_fma_f32 v93, v51, v139, v69
	v_fma_f32 v91, v52, v140, v69
	v_fma_f32 v89, v53, v141, v69
	v_fma_f32 v87, v54, v142, v69
	v_fma_f32 v85, v55, v143, v69
	v_fma_f32 v83, v56, v144, v69
	v_fma_f32 v75, v57, v145, v69
	v_fma_f32 v74, v58, v146, v69
	v_fma_f32 v73, v59, v147, v69
	v_fma_f32 v72, v60, v148, v69
	v_fma_f32 v71, v61, v149, v69
	v_fma_f32 v70, v62, v150, v69
	v_fmac_f32_e32 v69, v63, v128
	s_waitcnt vmcnt(2)
	v_fma_f32 v62, v32, v136, v67
	v_fma_f32 v61, v33, v137, v67
	v_fma_f32 v60, v34, v138, v67
	v_fma_f32 v59, v35, v139, v67
	v_fma_f32 v58, v36, v140, v67
	v_fma_f32 v57, v37, v141, v67
	v_fma_f32 v56, v38, v142, v67
	v_fma_f32 v55, v39, v143, v67
	v_fma_f32 v54, v40, v144, v67
	v_fma_f32 v53, v41, v145, v67
	v_fma_f32 v52, v42, v146, v67
	v_fma_f32 v51, v43, v147, v67
	v_fma_f32 v50, v44, v148, v67
	v_fma_f32 v49, v45, v149, v67
	v_fma_f32 v48, v46, v150, v67
	v_fmac_f32_e32 v67, v47, v128
	s_waitcnt vmcnt(1)
	v_fma_f32 v47, v16, v136, v66
	v_fma_f32 v46, v17, v137, v66
	v_fma_f32 v45, v18, v138, v66
	v_fma_f32 v44, v19, v139, v66
	v_fma_f32 v43, v20, v140, v66
	v_fma_f32 v42, v21, v141, v66
	v_fma_f32 v41, v22, v142, v66
	v_fma_f32 v40, v23, v143, v66
	v_fma_f32 v39, v24, v144, v66
	v_fma_f32 v38, v25, v145, v66
	v_fma_f32 v37, v26, v146, v66
	v_fma_f32 v36, v27, v147, v66
	v_fma_f32 v35, v28, v148, v66
	v_fma_f32 v34, v29, v149, v66
	v_fma_f32 v33, v30, v150, v66
	v_fmac_f32_e32 v66, v31, v128
	s_waitcnt vmcnt(0)
	v_fma_f32 v30, v0, v136, v65
	v_fma_f32 v29, v1, v137, v65
	v_fma_f32 v26, v2, v138, v65
	v_fma_f32 v25, v3, v139, v65
	v_fma_f32 v22, v4, v140, v65
	v_fma_f32 v21, v5, v141, v65
	v_fma_f32 v19, v6, v142, v65
	v_fma_f32 v18, v7, v143, v65
	v_fma_f32 v17, v8, v144, v65
	v_fma_f32 v16, v9, v145, v65
	v_fma_f32 v9, v10, v146, v65
	v_fma_f32 v8, v11, v147, v65
	v_fma_f32 v5, v12, v148, v65
	v_fma_f32 v4, v13, v149, v65
	v_fma_f32 v1, v14, v150, v65
	v_lshlrev_b32_e32 v32, 10, v82
	v_lshlrev_b32_e32 v31, 10, v123
	v_lshlrev_b32_e32 v28, 10, v125
	v_lshlrev_b32_e32 v27, 10, v127
	v_lshlrev_b32_e32 v24, 10, v84
	v_lshlrev_b32_e32 v23, 10, v68
	v_lshlrev_b32_e32 v20, 10, v129
	v_lshlrev_b32_e32 v14, 10, v130
	v_lshlrev_b32_e32 v13, 10, v86
	v_lshlrev_b32_e32 v12, 10, v88
	v_lshlrev_b32_e32 v11, 10, v131
	v_lshlrev_b32_e32 v10, 10, v132
	v_lshlrev_b32_e32 v7, 10, v90
	v_lshlrev_b32_e32 v6, 10, v92
	v_lshlrev_b32_e32 v3, 10, v133
	v_lshlrev_b32_e32 v2, 10, v134
	s_cbranch_scc0 .LBB0_1452
	v_add_u32_e32 v0, s60, v96
	v_add_u32_e32 v130, v32, v0
	v_ashrrev_i32_e32 v131, 31, v130
	v_cvt_pk_bf16_f32 v63, v126, s0
	v_lshl_add_u64 v[130:131], v[130:131], 1, s[8:9]
	global_store_short v[130:131], v63, off sc1
	v_add_u32_e32 v130, v31, v0
	v_ashrrev_i32_e32 v131, 31, v130
	v_cvt_pk_bf16_f32 v63, v124, s0
	v_lshl_add_u64 v[130:131], v[130:131], 1, s[8:9]
	global_store_short v[130:131], v63, off sc1
	v_add_u32_e32 v130, v28, v0
	v_ashrrev_i32_e32 v131, 31, v130
	v_cvt_pk_bf16_f32 v63, v122, s0
	v_lshl_add_u64 v[130:131], v[130:131], 1, s[8:9]
	global_store_short v[130:131], v63, off sc1
	v_add_u32_e32 v130, v27, v0
	v_ashrrev_i32_e32 v131, 31, v130
	v_cvt_pk_bf16_f32 v63, v93, s0
	v_lshl_add_u64 v[130:131], v[130:131], 1, s[8:9]
	global_store_short v[130:131], v63, off sc1
	v_add_u32_e32 v130, v24, v0
	v_ashrrev_i32_e32 v131, 31, v130
	v_cvt_pk_bf16_f32 v63, v91, s0
	v_lshl_add_u64 v[130:131], v[130:131], 1, s[8:9]
	global_store_short v[130:131], v63, off sc1
	v_add_u32_e32 v130, v23, v0
	v_ashrrev_i32_e32 v131, 31, v130
	v_cvt_pk_bf16_f32 v63, v89, s0
	v_lshl_add_u64 v[130:131], v[130:131], 1, s[8:9]
	global_store_short v[130:131], v63, off sc1
	v_add_u32_e32 v130, v20, v0
	v_ashrrev_i32_e32 v131, 31, v130
	v_cvt_pk_bf16_f32 v63, v87, s0
	v_lshl_add_u64 v[130:131], v[130:131], 1, s[8:9]
	global_store_short v[130:131], v63, off sc1
	v_add_u32_e32 v130, v14, v0
	v_ashrrev_i32_e32 v131, 31, v130
	v_cvt_pk_bf16_f32 v63, v85, s0
	v_lshl_add_u64 v[130:131], v[130:131], 1, s[8:9]
	global_store_short v[130:131], v63, off sc1
	v_add_u32_e32 v130, v13, v0
	v_ashrrev_i32_e32 v131, 31, v130
	v_cvt_pk_bf16_f32 v63, v83, s0
	v_lshl_add_u64 v[130:131], v[130:131], 1, s[8:9]
	global_store_short v[130:131], v63, off sc1
	v_add_u32_e32 v130, v12, v0
	v_ashrrev_i32_e32 v131, 31, v130
	v_cvt_pk_bf16_f32 v63, v75, s0
	v_lshl_add_u64 v[130:131], v[130:131], 1, s[8:9]
	global_store_short v[130:131], v63, off sc1
	v_add_u32_e32 v130, v11, v0
	v_ashrrev_i32_e32 v131, 31, v130
	v_cvt_pk_bf16_f32 v63, v74, s0
	v_lshl_add_u64 v[130:131], v[130:131], 1, s[8:9]
	global_store_short v[130:131], v63, off sc1
	v_add_u32_e32 v130, v10, v0
	v_ashrrev_i32_e32 v131, 31, v130
	v_cvt_pk_bf16_f32 v63, v73, s0
	v_lshl_add_u64 v[130:131], v[130:131], 1, s[8:9]
	global_store_short v[130:131], v63, off sc1
	v_add_u32_e32 v130, v7, v0
	v_ashrrev_i32_e32 v131, 31, v130
	v_cvt_pk_bf16_f32 v63, v72, s0
	v_lshl_add_u64 v[130:131], v[130:131], 1, s[8:9]
	global_store_short v[130:131], v63, off sc1
	v_add_u32_e32 v130, v6, v0
	v_ashrrev_i32_e32 v131, 31, v130
	v_cvt_pk_bf16_f32 v63, v71, s0
	v_lshl_add_u64 v[130:131], v[130:131], 1, s[8:9]
	global_store_short v[130:131], v63, off sc1
	v_add_u32_e32 v130, v3, v0
	v_ashrrev_i32_e32 v131, 31, v130
	v_cvt_pk_bf16_f32 v63, v70, s0
	v_lshl_add_u64 v[130:131], v[130:131], 1, s[8:9]
	global_store_short v[130:131], v63, off sc1
	v_add_u32_e32 v130, v2, v0
	v_ashrrev_i32_e32 v131, 31, v130
	v_cvt_pk_bf16_f32 v63, v69, s0
	v_lshl_add_u64 v[130:131], v[130:131], 1, s[8:9]
	global_store_short v[130:131], v63, off sc1
	v_or_b32_e32 v63, 32, v0
	v_add_u32_e32 v130, v32, v63
	v_ashrrev_i32_e32 v131, 31, v130
	v_cvt_pk_bf16_f32 v68, v62, s0
	v_lshl_add_u64 v[130:131], v[130:131], 1, s[8:9]
	global_store_short v[130:131], v68, off sc1
	v_add_u32_e32 v130, v31, v63
	v_ashrrev_i32_e32 v131, 31, v130
	v_cvt_pk_bf16_f32 v68, v61, s0
	v_lshl_add_u64 v[130:131], v[130:131], 1, s[8:9]
	global_store_short v[130:131], v68, off sc1
	v_add_u32_e32 v130, v28, v63
	v_ashrrev_i32_e32 v131, 31, v130
	v_cvt_pk_bf16_f32 v68, v60, s0
	v_lshl_add_u64 v[130:131], v[130:131], 1, s[8:9]
	global_store_short v[130:131], v68, off sc1
	v_add_u32_e32 v130, v27, v63
	v_ashrrev_i32_e32 v131, 31, v130
	v_cvt_pk_bf16_f32 v68, v59, s0
	v_lshl_add_u64 v[130:131], v[130:131], 1, s[8:9]
	global_store_short v[130:131], v68, off sc1
	v_add_u32_e32 v130, v24, v63
	v_ashrrev_i32_e32 v131, 31, v130
	v_cvt_pk_bf16_f32 v68, v58, s0
	v_lshl_add_u64 v[130:131], v[130:131], 1, s[8:9]
	global_store_short v[130:131], v68, off sc1
	v_add_u32_e32 v130, v23, v63
	v_ashrrev_i32_e32 v131, 31, v130
	v_cvt_pk_bf16_f32 v68, v57, s0
	v_lshl_add_u64 v[130:131], v[130:131], 1, s[8:9]
	global_store_short v[130:131], v68, off sc1
	v_add_u32_e32 v130, v20, v63
	v_ashrrev_i32_e32 v131, 31, v130
	v_cvt_pk_bf16_f32 v68, v56, s0
	v_lshl_add_u64 v[130:131], v[130:131], 1, s[8:9]
	global_store_short v[130:131], v68, off sc1
	v_add_u32_e32 v130, v14, v63
	v_ashrrev_i32_e32 v131, 31, v130
	v_cvt_pk_bf16_f32 v68, v55, s0
	v_lshl_add_u64 v[130:131], v[130:131], 1, s[8:9]
	global_store_short v[130:131], v68, off sc1
	v_add_u32_e32 v130, v13, v63
	v_ashrrev_i32_e32 v131, 31, v130
	v_cvt_pk_bf16_f32 v68, v54, s0
	v_lshl_add_u64 v[130:131], v[130:131], 1, s[8:9]
	global_store_short v[130:131], v68, off sc1
	v_add_u32_e32 v130, v12, v63
	v_ashrrev_i32_e32 v131, 31, v130
	v_cvt_pk_bf16_f32 v68, v53, s0
	v_lshl_add_u64 v[130:131], v[130:131], 1, s[8:9]
	global_store_short v[130:131], v68, off sc1
	v_add_u32_e32 v130, v11, v63
	v_ashrrev_i32_e32 v131, 31, v130
	v_cvt_pk_bf16_f32 v68, v52, s0
	v_lshl_add_u64 v[130:131], v[130:131], 1, s[8:9]
	global_store_short v[130:131], v68, off sc1
	v_add_u32_e32 v130, v10, v63
	v_ashrrev_i32_e32 v131, 31, v130
	v_cvt_pk_bf16_f32 v68, v51, s0
	v_lshl_add_u64 v[130:131], v[130:131], 1, s[8:9]
	global_store_short v[130:131], v68, off sc1
	v_add_u32_e32 v130, v7, v63
	v_ashrrev_i32_e32 v131, 31, v130
	v_cvt_pk_bf16_f32 v68, v50, s0
	v_lshl_add_u64 v[130:131], v[130:131], 1, s[8:9]
	global_store_short v[130:131], v68, off sc1
	v_add_u32_e32 v130, v6, v63
	v_ashrrev_i32_e32 v131, 31, v130
	v_cvt_pk_bf16_f32 v68, v49, s0
	v_lshl_add_u64 v[130:131], v[130:131], 1, s[8:9]
	global_store_short v[130:131], v68, off sc1
	v_add_u32_e32 v130, v3, v63
	v_ashrrev_i32_e32 v131, 31, v130
	v_cvt_pk_bf16_f32 v68, v48, s0
	v_lshl_add_u64 v[130:131], v[130:131], 1, s[8:9]
	global_store_short v[130:131], v68, off sc1
	v_add_u32_e32 v130, v2, v63
	v_ashrrev_i32_e32 v131, 31, v130
	v_cvt_pk_bf16_f32 v68, v67, s0
	v_lshl_add_u64 v[130:131], v[130:131], 1, s[8:9]
	v_or_b32_e32 v63, 64, v0
	global_store_short v[130:131], v68, off sc1
	v_add_u32_e32 v130, v32, v63
	v_ashrrev_i32_e32 v131, 31, v130
	v_cvt_pk_bf16_f32 v68, v47, s0
	v_lshl_add_u64 v[130:131], v[130:131], 1, s[8:9]
	global_store_short v[130:131], v68, off sc1
	v_add_u32_e32 v130, v31, v63
	v_ashrrev_i32_e32 v131, 31, v130
	v_cvt_pk_bf16_f32 v68, v46, s0
	v_lshl_add_u64 v[130:131], v[130:131], 1, s[8:9]
	global_store_short v[130:131], v68, off sc1
	v_add_u32_e32 v130, v28, v63
	v_ashrrev_i32_e32 v131, 31, v130
	v_cvt_pk_bf16_f32 v68, v45, s0
	v_lshl_add_u64 v[130:131], v[130:131], 1, s[8:9]
	global_store_short v[130:131], v68, off sc1
	v_add_u32_e32 v130, v27, v63
	v_ashrrev_i32_e32 v131, 31, v130
	v_cvt_pk_bf16_f32 v68, v44, s0
	v_lshl_add_u64 v[130:131], v[130:131], 1, s[8:9]
	global_store_short v[130:131], v68, off sc1
	v_add_u32_e32 v130, v24, v63
	v_ashrrev_i32_e32 v131, 31, v130
	v_cvt_pk_bf16_f32 v68, v43, s0
	v_lshl_add_u64 v[130:131], v[130:131], 1, s[8:9]
	global_store_short v[130:131], v68, off sc1
	v_add_u32_e32 v130, v23, v63
	v_ashrrev_i32_e32 v131, 31, v130
	v_cvt_pk_bf16_f32 v68, v42, s0
	v_lshl_add_u64 v[130:131], v[130:131], 1, s[8:9]
	global_store_short v[130:131], v68, off sc1
	v_add_u32_e32 v130, v20, v63
	v_ashrrev_i32_e32 v131, 31, v130
	v_cvt_pk_bf16_f32 v68, v41, s0
	v_lshl_add_u64 v[130:131], v[130:131], 1, s[8:9]
	global_store_short v[130:131], v68, off sc1
	v_add_u32_e32 v130, v14, v63
	v_ashrrev_i32_e32 v131, 31, v130
	v_cvt_pk_bf16_f32 v68, v40, s0
	v_lshl_add_u64 v[130:131], v[130:131], 1, s[8:9]
	global_store_short v[130:131], v68, off sc1
	v_add_u32_e32 v130, v13, v63
	v_ashrrev_i32_e32 v131, 31, v130
	v_cvt_pk_bf16_f32 v68, v39, s0
	v_lshl_add_u64 v[130:131], v[130:131], 1, s[8:9]
	global_store_short v[130:131], v68, off sc1
	v_add_u32_e32 v130, v12, v63
	v_ashrrev_i32_e32 v131, 31, v130
	v_cvt_pk_bf16_f32 v68, v38, s0
	v_lshl_add_u64 v[130:131], v[130:131], 1, s[8:9]
	global_store_short v[130:131], v68, off sc1
	v_add_u32_e32 v130, v11, v63
	v_ashrrev_i32_e32 v131, 31, v130
	v_cvt_pk_bf16_f32 v68, v37, s0
	v_lshl_add_u64 v[130:131], v[130:131], 1, s[8:9]
	global_store_short v[130:131], v68, off sc1
	v_add_u32_e32 v130, v10, v63
	v_ashrrev_i32_e32 v131, 31, v130
	v_cvt_pk_bf16_f32 v68, v36, s0
	v_lshl_add_u64 v[130:131], v[130:131], 1, s[8:9]
	global_store_short v[130:131], v68, off sc1
	v_add_u32_e32 v130, v7, v63
	v_ashrrev_i32_e32 v131, 31, v130
	v_cvt_pk_bf16_f32 v68, v35, s0
	v_lshl_add_u64 v[130:131], v[130:131], 1, s[8:9]
	global_store_short v[130:131], v68, off sc1
	v_add_u32_e32 v130, v6, v63
	v_ashrrev_i32_e32 v131, 31, v130
	v_cvt_pk_bf16_f32 v68, v34, s0
	v_lshl_add_u64 v[130:131], v[130:131], 1, s[8:9]
	global_store_short v[130:131], v68, off sc1
	v_add_u32_e32 v130, v3, v63
	v_ashrrev_i32_e32 v131, 31, v130
	v_cvt_pk_bf16_f32 v68, v33, s0
	v_lshl_add_u64 v[130:131], v[130:131], 1, s[8:9]
	global_store_short v[130:131], v68, off sc1
	v_add_u32_e32 v130, v2, v63
	v_ashrrev_i32_e32 v131, 31, v130
	v_cvt_pk_bf16_f32 v68, v66, s0
	v_lshl_add_u64 v[130:131], v[130:131], 1, s[8:9]
	v_or_b32_e32 v0, 0x60, v0
	global_store_short v[130:131], v68, off sc1
	v_add_u32_e32 v130, v32, v0
	v_ashrrev_i32_e32 v131, 31, v130
	v_cvt_pk_bf16_f32 v63, v30, s0
	v_lshl_add_u64 v[130:131], v[130:131], 1, s[8:9]
	global_store_short v[130:131], v63, off sc1
	v_add_u32_e32 v130, v31, v0
	v_ashrrev_i32_e32 v131, 31, v130
	v_cvt_pk_bf16_f32 v63, v29, s0
	v_lshl_add_u64 v[130:131], v[130:131], 1, s[8:9]
	global_store_short v[130:131], v63, off sc1
	v_add_u32_e32 v130, v28, v0
	v_ashrrev_i32_e32 v131, 31, v130
	v_cvt_pk_bf16_f32 v63, v26, s0
	v_lshl_add_u64 v[130:131], v[130:131], 1, s[8:9]
	global_store_short v[130:131], v63, off sc1
	v_add_u32_e32 v130, v27, v0
	v_ashrrev_i32_e32 v131, 31, v130
	v_cvt_pk_bf16_f32 v63, v25, s0
	v_lshl_add_u64 v[130:131], v[130:131], 1, s[8:9]
	global_store_short v[130:131], v63, off sc1
	v_add_u32_e32 v130, v24, v0
	v_ashrrev_i32_e32 v131, 31, v130
	v_cvt_pk_bf16_f32 v63, v22, s0
	v_lshl_add_u64 v[130:131], v[130:131], 1, s[8:9]
	global_store_short v[130:131], v63, off sc1
	v_add_u32_e32 v130, v23, v0
	v_ashrrev_i32_e32 v131, 31, v130
	v_cvt_pk_bf16_f32 v63, v21, s0
	v_lshl_add_u64 v[130:131], v[130:131], 1, s[8:9]
	global_store_short v[130:131], v63, off sc1
	v_add_u32_e32 v130, v20, v0
	v_ashrrev_i32_e32 v131, 31, v130
	v_cvt_pk_bf16_f32 v63, v19, s0
	v_lshl_add_u64 v[130:131], v[130:131], 1, s[8:9]
	global_store_short v[130:131], v63, off sc1
	v_add_u32_e32 v130, v14, v0
	v_ashrrev_i32_e32 v131, 31, v130
	v_cvt_pk_bf16_f32 v63, v18, s0
	v_lshl_add_u64 v[130:131], v[130:131], 1, s[8:9]
	global_store_short v[130:131], v63, off sc1
	v_add_u32_e32 v130, v13, v0
	v_ashrrev_i32_e32 v131, 31, v130
	v_cvt_pk_bf16_f32 v63, v17, s0
	v_lshl_add_u64 v[130:131], v[130:131], 1, s[8:9]
	global_store_short v[130:131], v63, off sc1
	v_add_u32_e32 v130, v12, v0
	v_ashrrev_i32_e32 v131, 31, v130
	v_cvt_pk_bf16_f32 v63, v16, s0
	v_lshl_add_u64 v[130:131], v[130:131], 1, s[8:9]
	global_store_short v[130:131], v63, off sc1
	v_add_u32_e32 v130, v11, v0
	v_ashrrev_i32_e32 v131, 31, v130
	v_cvt_pk_bf16_f32 v63, v9, s0
	v_lshl_add_u64 v[130:131], v[130:131], 1, s[8:9]
	global_store_short v[130:131], v63, off sc1
	v_add_u32_e32 v130, v10, v0
	v_ashrrev_i32_e32 v131, 31, v130
	v_cvt_pk_bf16_f32 v63, v8, s0
	v_lshl_add_u64 v[130:131], v[130:131], 1, s[8:9]
	global_store_short v[130:131], v63, off sc1
	v_add_u32_e32 v130, v7, v0
	v_ashrrev_i32_e32 v131, 31, v130
	v_cvt_pk_bf16_f32 v63, v5, s0
	v_lshl_add_u64 v[130:131], v[130:131], 1, s[8:9]
	global_store_short v[130:131], v63, off sc1
	v_add_u32_e32 v130, v6, v0
	v_ashrrev_i32_e32 v131, 31, v130
	v_cvt_pk_bf16_f32 v63, v4, s0
	v_lshl_add_u64 v[130:131], v[130:131], 1, s[8:9]
	global_store_short v[130:131], v63, off sc1
	v_add_u32_e32 v130, v3, v0
	v_ashrrev_i32_e32 v131, 31, v130
	v_cvt_pk_bf16_f32 v63, v1, s0
	v_lshl_add_u64 v[130:131], v[130:131], 1, s[8:9]
	global_store_short v[130:131], v63, off sc1
	v_add_u32_e32 v0, v2, v0
	s_mov_b64 s[62:63], 0
